# seams 2-9: the s_sleep between successive polls of the per-XCD and cross-XCD counters removed (back-to-back sc1 polls); on top of all66
# baseline (speedup 1.0000x reference)
; __device__ __forceinline__ unsigned xb_ld(unsigned* p)              { return __hip_atomic_load(p, __ATOMIC_RELAXED, __HIP_MEMORY_SCOPE_AGENT); }
; __device__ __forceinline__ unsigned xb_add(unsigned* p, unsigned v) { return __hip_atomic_fetch_add(p, v, __ATOMIC_RELAXED, __HIP_MEMORY_SCOPE_AGENT); }
; #define XB_SPIN(cond, bar) do { unsigned _sp = 0; while (cond) { __builtin_amdgcn_s_sleep(1); \
;     if ((++_sp & 255u) == 0u) { if (xb_ld(&(bar)[XB_TMO])) break; if (_sp > XB_SPIN_CAP) { atomicAdd(&(bar)[XB_TMO], 1u); break; } } } } while (0)
; __device__ __forceinline__ void xcd_barrier(const XcdBarrier& b, const int wid) {
;     ...
;         const unsigned old = xb_add(&bar[XB_XSUB(b.x)], 1u);
;         const unsigned gen = old / nloc;
;         if (old + 1u == (gen + 1u) * nloc) {
;             __builtin_amdgcn_fence(__ATOMIC_RELEASE, "agent");
;             asm volatile("s_waitcnt vmcnt(0)" ::: "memory");
;             const unsigned og = xb_add(&bar[XB_TOP], 1u);
;             const unsigned tg = og / nx;
;             if (og + 1u == (tg + 1u) * nx) xb_add(&bar[XB_TOPGEN], 1u);
;             else XB_SPIN(xb_ld(&bar[XB_TOPGEN]) == tg, bar);
;             __builtin_amdgcn_fence(__ATOMIC_ACQUIRE, "agent");
;             xb_add(&bar[XB_XGEN(b.x)], 1u);
;             asm volatile("s_waitcnt vmcnt(0)" ::: "memory");
;         } else {
;             XB_SPIN(xb_ld(&bar[XB_XGEN(b.x)]) == gen, bar);
.Lxb2_l:
	global_load_dword v6, v1, s[2:3] offset:1024 sc1
	s_sub_i32 s4, s4, 1
	s_waitcnt vmcnt(0)
	v_cmp_ge_u32_e32 vcc, v6, v2
	s_cbranch_vccnz .Lxb2_go
	s_cmp_eq_u32 s4, 0
	s_cbranch_scc1 .Lxb2_go
	s_branch .Lxb2_l

; __device__ __forceinline__ unsigned xb_ld(unsigned* p)              { return __hip_atomic_load(p, __ATOMIC_RELAXED, __HIP_MEMORY_SCOPE_AGENT); }
; __device__ __forceinline__ unsigned xb_add(unsigned* p, unsigned v) { return __hip_atomic_fetch_add(p, v, __ATOMIC_RELAXED, __HIP_MEMORY_SCOPE_AGENT); }
; #define XB_SPIN(cond, bar) do { unsigned _sp = 0; while (cond) { __builtin_amdgcn_s_sleep(1); \
;     if ((++_sp & 255u) == 0u) { if (xb_ld(&(bar)[XB_TMO])) break; if (_sp > XB_SPIN_CAP) { atomicAdd(&(bar)[XB_TMO], 1u); break; } } } } while (0)
; __device__ __forceinline__ void xcd_barrier(const XcdBarrier& b, const int wid) {
;     ...
;             const unsigned og = xb_add(&bar[XB_TOP], 1u);
;             const unsigned tg = og / nx;
;             if (og + 1u == (tg + 1u) * nx) xb_add(&bar[XB_TOPGEN], 1u);
;             else XB_SPIN(xb_ld(&bar[XB_TOPGEN]) == tg, bar);
;             __builtin_amdgcn_fence(__ATOMIC_ACQUIRE, "agent");
.Lxb2_w:
	global_load_dword v6, v0, s[10:11] sc1
	s_sub_i32 s4, s4, 1
	s_waitcnt vmcnt(0)
	v_cmp_ge_u32_e32 vcc, v6, v3
	s_cbranch_vccnz .Lxb2_acq
	s_cmp_eq_u32 s4, 0
	s_cbranch_scc1 .Lxb2_acq
	s_branch .Lxb2_w
